# P4 items remapped to the XCD group that owns the row panel in P5; P4->P5 grid barrier XCD-local (v59 + p4remap, 6 local barriers)
# speedup vs baseline: 1.0042x; 1.0042x over previous
.LBB0_515:
	s_or_b64 exec, exec, s[4:5]
	s_waitcnt lgkmcnt(0)
	v_mov_b32_e32 v0, v192
	s_barrier
	s_mov_b64 s[6:7], s[0:1]
	v_readfirstlane_b32 s4, v0
	s_ashr_i32 s17, s4, 6
	s_add_i32 s16, s17, s3
	s_and_b32 s25, s2, 7
	s_lshl_b32 s25, s25, 12
	s_lshr_b32 s26, s2, 3
	s_lshl_b32 s26, s26, 7
	s_add_i32 s25, s25, s26
	s_add_i32 s26, s25, 0x80
	s_add_i32 s25, s25, s17
	s_mov_b32 s27, 8
	s_cmpk_eq_i32 s52, 0x100
	s_cselect_b32 s16, s25, s16
	s_cselect_b32 s26, s26, 0x8000
	s_cselect_b32 s27, s27, s46
	s_mov_b64 s[4:5], s[0:1]
	s_cmpk_gt_i32 s16, 0x7fff
	s_cbranch_scc1 .LBB0_518
	s_load_dwordx2 s[6:7], s[6:7], 0x80
	v_and_b32_e32 v18, 63, v0
	s_load_dwordx2 s[4:5], s[4:5], 0x30
	v_mov_b32_e32 v17, 0
	v_lshlrev_b32_e32 v16, 4, v18
	s_waitcnt lgkmcnt(0)
	s_add_u32 s8, s6, 0x19800000
	s_addc_u32 s9, s7, 0
	s_add_u32 s10, s6, 0xe600000
	s_addc_u32 s11, s7, 0
	s_add_u32 s12, s6, 0xc600000
	s_addc_u32 s13, s7, 0
	s_ashr_i32 s6, s16, 2
	s_ashr_i32 s7, s6, 31
	s_mul_i32 s19, s6, 0x3000
	s_mul_hi_i32 s18, s6, 0x3000
	s_add_u32 s19, s10, s19
	s_addc_u32 s20, s11, s18
	s_lshl_b32 s21, s17, 9
	s_lshl_b32 s17, s17, 10
	s_and_b32 s22, s17, 0xc00
	s_add_u32 s18, s19, s22
	s_addc_u32 s19, s20, 0
	s_lshl_b64 s[6:7], s[6:7], 12
	s_add_u32 s6, s8, s6
	s_addc_u32 s7, s9, s7
	v_lshl_add_u64 v[0:1], s[18:19], 0, v[16:17]
	s_movk_i32 s17, 0x2000
	s_add_u32 s6, s6, s22
	v_add_co_u32_e32 v0, vcc, s17, v0
	s_addc_u32 s7, s7, 0
	s_nop 0
	v_addc_co_u32_e32 v1, vcc, 0, v1, vcc
	global_load_dwordx4 v[12:15], v16, s[6:7] nt
	v_lshlrev_b32_e32 v16, 5, v18
	global_load_dwordx4 v[8:11], v[0:1], off nt
	s_nop 0
	global_load_dwordx4 v[0:3], v16, s[4:5]
	global_load_dwordx4 v[4:7], v16, s[4:5] offset:16
	v_mbcnt_lo_u32_b32 v16, -1, 0
	v_mbcnt_hi_u32_b32 v16, -1, v16
	v_and_b32_e32 v19, 64, v16
	v_add_u32_e32 v19, 64, v19
	v_xor_b32_e32 v20, 1, v16
	v_cmp_lt_i32_e32 vcc, v20, v19
	s_lshl_b32 s4, s2, 12
	s_add_i32 s18, s4, s21
	v_cndmask_b32_e32 v20, v16, v20, vcc
	v_lshlrev_b32_e32 v26, 2, v20
	v_xor_b32_e32 v20, 2, v16
	v_cmp_lt_i32_e32 vcc, v20, v19
	s_lshl_b32 s19, s52, 12
	s_waitcnt vmcnt(8)
	v_mov_b32_e32 v32, 0x358637bd
	v_cndmask_b32_e32 v20, v16, v20, vcc
	v_lshlrev_b32_e32 v27, 2, v20
	v_xor_b32_e32 v20, 4, v16
	v_cmp_lt_i32_e32 vcc, v20, v19
	s_mov_b32 s20, 0xf800000
	v_mov_b32_e32 v33, 0x260
	v_cndmask_b32_e32 v20, v16, v20, vcc
	v_lshlrev_b32_e32 v28, 2, v20
	v_xor_b32_e32 v20, 8, v16
	v_cmp_lt_i32_e32 vcc, v20, v19
	s_nop 1
	v_cndmask_b32_e32 v20, v16, v20, vcc
	v_lshlrev_b32_e32 v29, 2, v20
	v_xor_b32_e32 v20, 16, v16
	v_cmp_lt_i32_e32 vcc, v20, v19
	s_nop 1
	v_cndmask_b32_e32 v20, v16, v20, vcc
	v_lshlrev_b32_e32 v30, 2, v20
	v_xor_b32_e32 v20, 32, v16
	v_cmp_lt_i32_e32 vcc, v20, v19
	s_nop 1
	v_cndmask_b32_e32 v16, v16, v20, vcc
	v_lshlrev_b32_e32 v31, 2, v16
	v_lshlrev_b32_e32 v16, 4, v18
.LBB0_517:
	s_ashr_i32 s6, s16, 2
	s_add_i32 s7, s16, s27
	s_cmp_lt_i32 s7, s26
	s_cselect_b64 s[4:5], -1, 0
	s_waitcnt vmcnt(3)
	v_lshlrev_b32_e32 v21, 16, v15
	s_waitcnt vmcnt(2)
	v_lshlrev_b32_e32 v20, 16, v11
	v_and_b32_e32 v19, 0xffff0000, v15
	v_and_b32_e32 v18, 0xffff0000, v11
	v_lshlrev_b32_e32 v22, 16, v10
	v_and_b32_e32 v11, 0xffff0000, v14
	v_lshlrev_b32_e32 v15, 16, v13
	v_and_b32_e32 v24, 0xffff0000, v9
	v_lshlrev_b32_e32 v43, 16, v12
	s_and_b64 s[4:5], s[4:5], exec
	v_lshlrev_b32_e32 v23, 16, v14
	v_lshlrev_b32_e32 v14, 16, v9
	v_and_b32_e32 v25, 0xffff0000, v13
	v_and_b32_e32 v9, 0xffff0000, v12
	v_mul_f32_e32 v37, 0xbfb8aa3b, v22
	v_mov_b32_e32 v34, v19
	v_mov_b32_e32 v35, v11
	v_mul_f32_e32 v40, 0xbfb8aa3b, v24
	v_mul_f32_e32 v45, v15, v15
	v_mul_f32_e32 v46, v43, v43
	s_cselect_b32 s21, s7, s16
	v_mov_b32_e32 v12, v21
	v_mov_b32_e32 v13, v23
	v_exp_f32_e32 v37, v37
	v_pk_mul_f32 v[34:35], v[34:35], v[34:35]
	v_exp_f32_e32 v40, v40
	v_fmac_f32_e32 v45, v25, v25
	v_fmac_f32_e32 v46, v9, v9
	s_ashr_i32 s22, s21, 2
	v_and_b32_e32 v10, 0xffff0000, v10
	v_pk_fma_f32 v[12:13], v[12:13], v[12:13], v[34:35]
	v_add_f32_e32 v34, v46, v45
	s_ashr_i32 s23, s22, 31
	v_lshlrev_b32_e32 v42, 16, v8
	v_and_b32_e32 v8, 0xffff0000, v8
	v_mul_f32_e32 v36, 0xbfb8aa3b, v20
	v_mul_f32_e32 v38, 0xbfb8aa3b, v10
	v_mul_f32_e32 v39, 0xbfb8aa3b, v14
	v_add_f32_e32 v13, v13, v34
	s_mov_b32 s16, s7
	s_mul_hi_i32 s7, s22, 0x3000
	s_mul_i32 s24, s22, 0x3000
	s_lshl_b64 s[22:23], s[22:23], 12
	v_mul_f32_e32 v44, 0xbfb8aa3b, v8
	v_exp_f32_e32 v36, v36
	v_exp_f32_e32 v38, v38
	v_exp_f32_e32 v39, v39
	v_add_f32_e32 v13, v12, v13
	s_add_u32 s22, s8, s22
	v_exp_f32_e32 v44, v44
	v_add_f32_e32 v34, 1.0, v37
	v_add_f32_e32 v37, 1.0, v40
	ds_bpermute_b32 v40, v26, v13
	s_addc_u32 s23, s9, s23
	s_lshl_b32 s21, s21, 10
	s_and_b32 s21, s21, 0xc00
	v_mul_f32_e32 v41, 0xbfb8aa3b, v42
	s_add_u32 s22, s22, s21
	v_exp_f32_e32 v41, v41
	v_add_f32_e32 v12, 1.0, v36
	v_add_f32_e32 v35, 1.0, v38
	v_add_f32_e32 v36, 1.0, v39
	s_addc_u32 s23, s23, 0
	v_add_f32_e32 v39, 1.0, v44
	v_rcp_f32_e32 v44, v34
	v_rcp_f32_e32 v46, v35
	v_rcp_f32_e32 v48, v36
	v_rcp_f32_e32 v50, v37
	global_load_dwordx4 v[34:37], v16, s[22:23] nt
	s_add_u32 s22, s10, s24
	s_waitcnt lgkmcnt(0)
	v_add_f32_e32 v13, v13, v40
	s_addc_u32 s7, s11, s7
	ds_bpermute_b32 v40, v27, v13
	s_add_u32 s22, s22, s21
	v_add_f32_e32 v38, 1.0, v41
	s_addc_u32 s23, s7, 0
	v_rcp_f32_e32 v52, v38
	v_rcp_f32_e32 v54, v39
	v_lshl_add_u64 v[38:39], s[22:23], 0, v[16:17]
	v_add_co_u32_e32 v38, vcc, s17, v38
	s_waitcnt lgkmcnt(0)
	v_add_f32_e32 v13, v13, v40
	v_addc_co_u32_e32 v39, vcc, 0, v39, vcc
	global_load_dwordx4 v[38:41], v[38:39], off nt
	ds_bpermute_b32 v45, v28, v13
	v_mul_f32_e32 v47, 0xbfb8aa3b, v18
	v_exp_f32_e32 v47, v47
	s_ashr_i32 s7, s6, 31
	s_lshl_b64 s[6:7], s[6:7], 12
	s_waitcnt lgkmcnt(0)
	v_add_f32_e32 v13, v13, v45
	ds_bpermute_b32 v45, v29, v13
	s_add_u32 s6, s12, s6
	s_addc_u32 s7, s13, s7
	s_and_b32 s21, s18, 0x600
	v_add_f32_e32 v56, 1.0, v47
	s_waitcnt lgkmcnt(0)
	v_add_f32_e32 v13, v13, v45
	ds_bpermute_b32 v45, v30, v13
	s_lshl_b32 s21, s21, 1
	s_add_u32 s22, s6, s21
	s_addc_u32 s23, s7, 0
	v_rcp_f32_e32 v12, v12
	s_waitcnt lgkmcnt(0)
	v_add_f32_e32 v13, v13, v45
	ds_bpermute_b32 v45, v31, v13
	s_add_i32 s18, s18, s19
	s_waitcnt lgkmcnt(0)
	v_add_f32_e32 v13, v13, v45
	v_fmamk_f32 v13, v13, 0x3b000000, v32
	v_mul_f32_e32 v45, 0x4f800000, v13
	v_cmp_gt_f32_e32 vcc, s20, v13
	s_nop 1
	v_cndmask_b32_e32 v13, v13, v45, vcc
	v_sqrt_f32_e32 v45, v13
	s_nop 0
	v_add_u32_e32 v47, -1, v45
	v_add_u32_e32 v49, 1, v45
	v_fma_f32 v51, -v47, v45, v13
	v_fma_f32 v53, -v49, v45, v13
	v_cmp_ge_f32_e64 s[6:7], 0, v51
	s_nop 1
	v_cndmask_b32_e64 v45, v45, v47, s[6:7]
	v_cmp_lt_f32_e64 s[6:7], 0, v53
	s_nop 1
	v_cndmask_b32_e64 v45, v45, v49, s[6:7]
	v_mul_f32_e32 v47, 0x37800000, v45
	v_cndmask_b32_e32 v45, v45, v47, vcc
	v_cmp_class_f32_e32 vcc, v13, v33
	s_nop 1
	v_cndmask_b32_e32 v13, v45, v13, vcc
	v_div_scale_f32 v45, s[6:7], v13, v13, 1.0
	v_rcp_f32_e32 v49, v45
	v_div_scale_f32 v47, vcc, 1.0, v13, 1.0
	v_fma_f32 v51, -v45, v49, 1.0
	v_fmac_f32_e32 v49, v51, v49
	v_mul_f32_e32 v51, v47, v49
	v_fma_f32 v53, -v45, v51, v47
	v_fmac_f32_e32 v51, v53, v49
	v_fma_f32 v45, -v45, v51, v47
	v_div_fmas_f32 v45, v45, v49, v51
	v_div_fixup_f32 v53, v45, v13, 1.0
	v_pk_mul_f32 v[42:43], v[52:53], v[42:43]
	v_rcp_f32_e32 v52, v56
	v_mov_b32_e32 v47, v53
	v_mov_b32_e32 v13, v53
	v_mov_b32_e32 v55, v53
	v_mov_b32_e32 v49, v53
	v_pk_mul_f32 v[10:11], v[46:47], v[10:11]
	v_pk_mul_f32 v[12:13], v[12:13], v[20:21]
	v_mov_b32_e32 v51, v53
	v_mov_b32_e32 v45, v53
	v_pk_mul_f32 v[8:9], v[54:55], v[8:9]
	v_pk_mul_f32 v[14:15], v[48:49], v[14:15]
	s_waitcnt vmcnt(2)
	v_mul_f32_e32 v11, v5, v11
	v_mul_f32_e32 v13, v6, v13
	v_pk_mul_f32 v[24:25], v[50:51], v[24:25]
	v_pk_mul_f32 v[22:23], v[44:45], v[22:23]
	v_mul_f32_e32 v9, v1, v9
	v_mul_f32_e32 v15, v2, v15
	v_mul_f32_e32 v10, v10, v11
	v_mul_f32_e32 v11, v12, v13
	v_pk_mul_f32 v[12:13], v[52:53], v[18:19]
	v_mul_f32_e32 v43, v0, v43
	v_mul_f32_e32 v21, v3, v25
	v_mul_f32_e32 v23, v4, v23
	v_mul_f32_e32 v8, v8, v9
	v_mul_f32_e32 v9, v14, v15
	v_mul_f32_e32 v13, v7, v13
	v_mul_f32_e32 v20, v42, v43
	v_mul_f32_e32 v14, v24, v21
	v_mul_f32_e32 v15, v22, v23
	v_cvt_pk_bf16_f32 v8, v20, v8
	v_cvt_pk_bf16_f32 v9, v9, v14
	v_cvt_pk_bf16_f32 v10, v15, v10
	v_mul_f32_e32 v12, v12, v13
	v_cvt_pk_bf16_f32 v11, v11, v12
	global_store_dwordx4 v16, v[8:11], s[22:23]
	s_waitcnt vmcnt(2)
	v_mov_b64_e32 v[12:13], v[34:35]
	v_mov_b64_e32 v[14:15], v[36:37]
	s_waitcnt vmcnt(1)
	v_mov_b64_e32 v[8:9], v[38:39]
	v_mov_b64_e32 v[10:11], v[40:41]
	s_mov_b64 vcc, s[4:5]
	s_cbranch_vccnz .LBB0_517

.LBB0_550:
	s_andn2_saveexec_b64 s[10:11], s[10:11]
	s_cbranch_execz .LBB0_570
	s_waitcnt lgkmcnt(0)
	s_cmp_lg_u32 s99, 0
	s_cbranch_scc1 .Lxcd_local_1
	s_mov_b64 s[10:11], exec
	buffer_wbl2 sc1
	s_waitcnt lgkmcnt(0)
	s_waitcnt vmcnt(0)
	v_mbcnt_lo_u32_b32 v1, s10, 0
	v_mbcnt_hi_u32_b32 v1, s11, v1
	v_cmp_eq_u32_e32 vcc, 0, v1
	s_and_saveexec_b64 s[12:13], vcc
	s_cbranch_execz .LBB0_553
	s_bcnt1_i32_b64 s10, s[10:11]
	v_mov_b32_e32 v2, 0x7000
	v_mov_b32_e32 v3, s10
	global_atomic_add v2, v2, v3, s[6:7] offset:1024 sc0

.Lxcd_local_1:
	s_mov_b64 s[6:7], exec
	v_mbcnt_lo_u32_b32 v0, s6, 0
	v_mbcnt_hi_u32_b32 v0, s7, v0
	v_cmp_eq_u32_e32 vcc, 0, v0
	s_waitcnt vmcnt(0)
	buffer_inv sc1
	s_and_saveexec_b64 s[10:11], vcc
	s_cbranch_execz .LBB0_569
	s_bcnt1_i32_b64 s6, s[6:7]
	v_mov_b32_e32 v0, 0x2000
	v_mov_b32_e32 v1, s6
	global_atomic_add v0, v1, s[8:9] offset:1024
